# FFN-up GEMM: the 168 workgroups that own 11 tiles (one tile of slack) start half a tile (~31 us) late, desynchronising their epilogue store bursts from the 12-tile workgroups
# baseline (speedup 1.0000x reference)
.LBB0_1088:
	s_waitcnt vmcnt(0)
	s_cmpk_lt_i32 s3, 0x58
	s_cbranch_scc1 .Lp8_nodelay
	s_mov_b32 s4, 8
.Lp8_dly:
	s_sleep 127
	s_sub_u32 s4, s4, 1
	s_cmp_lg_u32 s4, 0
	s_cbranch_scc1 .Lp8_dly
.Lp8_nodelay:
	v_and_b32_e32 v10, 0x3ff, v0
	s_cmpk_lt_i32 s3, 0xb58
	s_cselect_b64 s[4:5], -1, 0
	s_cmpk_gt_i32 s3, 0xb57
	v_readfirstlane_b32 s54, v10
	s_cbranch_scc1 .LBB0_1090
	s_ashr_i32 s6, s3, 31
	s_lshr_b32 s6, s6, 29
	s_add_i32 s6, s3, s6
	s_ashr_i32 s7, s6, 3
	s_and_b32 s6, s6, -8
	s_sub_i32 s6, s3, s6
	s_cmp_lt_i32 s6, 0
	s_movk_i32 s8, 0x16c
	s_cselect_b32 s8, s8, 0x16b
	s_mul_i32 s6, s6, s8
	s_add_i32 s6, s6, s7
	s_mul_hi_i32 s7, s6, 0x2e8ba2e9
	s_lshr_b32 s8, s7, 31
	s_ashr_i32 s7, s7, 4
	s_add_i32 s7, s7, s8
	s_lshl_b32 s8, s7, 1
	s_mulk_i32 s7, 0x58
	s_sub_i32 s6, s6, s7
	s_bfe_u32 s7, s6, 0x10007
	s_add_i32 s7, s6, s7
	s_bfe_i32 s9, s7, 0x80000
	s_and_b32 s7, s7, 0xfe
	s_sub_i32 s6, s6, s7
	s_sext_i32_i16 s9, s9
	s_sext_i32_i8 s6, s6
	s_add_i32 s20, s8, s6
	s_ashr_i32 s46, s9, 1
